# attention: lazy softmax rescale - the running max stays the exp2 reference until a lane's new max exceeds it by 8 (exact algebra, p <= 256), so the O/l rescale block runs rarely
# speedup vs baseline: 1.0488x; 1.0116x over previous
; template <int DV, int MODE>
; DI void attn_item(const AttnArgs& a, char* smem) {
;     ...
;     __syncthreads();
;     *(u32x4*)(Ks1 + srow * 72 + sch * 8) = rk1;
;     if (MODE == 1) *(u32x4*)(Ks2 + srow * 72 + sch * 8) = rk2;
; #pragma unroll
;     for (int j = 0; j < NVL; ++j) *(u32x4*)(Vs + (srow + 64 * j) * 72 + sch * 8) = rv[j];
;     __syncthreads();
;     if (tt + 1 < nt) ATTN_FETCH(tt + 1)
;     ...
;       f32x16 s[2];
; #pragma unroll
;       for (int kb = 0; kb < 2; ++kb) {
; #pragma unroll
;         for (int i = 0; i < 16; ++i) s[kb][i] = 0.f;
; #pragma unroll
;         for (int ks = 0; ks < 4; ++ks) {
;           const bf8 kf = *(const bf8*)(Ks + (kb * 32 + r) * 72 + ks * 16 + h * 8);
;           s[kb] = mfma32(kf, qf[ks], s[kb]);
;         }
;       }
;       constexpr float SC = 0.125f * LOG2E;
;       float mx = -INFINITY;
;       if (local) {
; #pragma unroll
;         for (int kb = 0; kb < 2; ++kb)
; #pragma unroll
;           for (int i = 0; i < 16; ++i) {
;             const int kc = kb * 32 + crow(i, h);
;             const bool ok = (kc >= cs) && (kc < cs + 16);
;             const int dc = kc - qc + 15;
;             const int dr = kr - rq + 7;
;             const float bias = rpbS[dr * 32 + (ok ? dc : 0)];
;             const float v = ok ? (s[kb][i] + bias * (1.f / SC)) : -INFINITY;
;             s[kb][i] = v;
;             mx = fmaxf(mx, v);
;           }
;       } else {
; #pragma unroll
;         for (int kb = 0; kb < 2; ++kb)
; #pragma unroll
;           for (int i = 0; i < 16; i += 2) mx = fmaxf(fmaxf(mx, s[kb][i]), s[kb][i + 1]);
;       }
;       mx = fmaxf(mx, shx(mx, lane, 32)) * SC;
;       const float mn = fmaxf(m, mx);
;       const bool resc = __builtin_amdgcn_ballot_w64(mn != m) != 0ull;
;       float ps0 = 0.f, ps1 = 0.f;
; #pragma unroll
;       for (int kb = 0; kb < 2; ++kb)
; #pragma unroll
;         for (int i = 0; i < 16; i += 2) {
;           f32x2n v = {s[kb][i], s[kb][i + 1]};
;           v = v * f32x2n{SC, SC} - f32x2n{mn, mn};
;           const float p0 = ex2(v.x), p1 = ex2(v.y);
;           s[kb][i] = p0; s[kb][i + 1] = p1;
;           ps0 += p0; ps1 += p1;
;         }
;       if (resc) {
;         const float alpha = ex2(m - mn);
;         m = mn;
;         lsum *= alpha;
; #pragma unroll
;         for (int d = 0; d < NDV; ++d)
; #pragma unroll
;           for (int i = 0; i < 16; ++i) O[d][i] *= alpha;
;       }
.LBB0_415:
	v_lshl_add_u64 v[34:35], v[98:99], 0, s[2:3]
	s_barrier
	s_waitcnt vmcnt(1)
	ds_write_b128 v94, v[82:85]
	s_waitcnt vmcnt(0)
	ds_write_b128 v94, v[86:89] offset:18432
	s_waitcnt lgkmcnt(0)
	s_barrier
	global_load_dwordx4 v[82:85], v[96:97], off
	global_load_dwordx4 v[86:89], v[34:35], off
	v_add_u32_e32 v103, v92, v102
	ds_read_b128 v[34:37], v103
	ds_read_b128 v[38:41], v103 offset:32
	ds_read_b128 v[106:109], v103 offset:4640
	s_waitcnt lgkmcnt(2)
	v_mfma_f32_32x32x16_bf16 v[50:65], v[34:37], v[78:81], 0
	ds_read_b128 v[34:37], v103 offset:64
	s_waitcnt lgkmcnt(2)
	v_mfma_f32_32x32x16_bf16 v[50:65], v[38:41], v[74:77], v[50:65]
	s_waitcnt lgkmcnt(0)
	v_mfma_f32_32x32x16_bf16 v[50:65], v[34:37], v[70:73], v[50:65]
	ds_read_b128 v[34:37], v103 offset:96
	s_waitcnt lgkmcnt(0)
	v_mfma_f32_32x32x16_bf16 v[50:65], v[34:37], v[66:69], v[50:65]
	ds_read_b128 v[34:37], v103 offset:4608
	s_waitcnt lgkmcnt(0)
	v_mfma_f32_32x32x16_bf16 v[34:49], v[34:37], v[78:81], 0
	s_nop 8
	v_max3_f32 v100, v50, s33, v51
	v_max3_f32 v100, v100, v52, v53
	v_max3_f32 v100, v100, v54, v55
	v_max3_f32 v100, v100, v56, v57
	v_max3_f32 v100, v100, v58, v59
	v_max3_f32 v100, v100, v60, v61
	v_max3_f32 v100, v100, v62, v63
	v_mfma_f32_32x32x16_bf16 v[34:49], v[106:109], v[74:77], v[34:49]
	ds_read_b128 v[106:109], v103 offset:4672
	v_max3_f32 v100, v100, v64, v65
	s_waitcnt lgkmcnt(0)
	v_mfma_f32_32x32x16_bf16 v[34:49], v[106:109], v[70:73], v[34:49]
	ds_read_b128 v[106:109], v103 offset:4704
	s_waitcnt lgkmcnt(0)
	v_mfma_f32_32x32x16_bf16 v[34:49], v[106:109], v[66:69], v[34:49]
	s_nop 11
	v_max3_f32 v100, v100, v34, v35
	v_max3_f32 v100, v100, v36, v37
	v_max3_f32 v100, v100, v38, v39
	v_max3_f32 v100, v100, v40, v41
	v_max3_f32 v100, v100, v42, v43
	v_max3_f32 v100, v100, v44, v45
	v_max3_f32 v100, v100, v46, v47
	v_max3_f32 v100, v100, v48, v49
	ds_bpermute_b32 v101, v93, v100
	s_waitcnt lgkmcnt(0)
	v_max_f32_e32 v101, v101, v101
	v_max_f32_e32 v100, v100, v101
	v_mul_f32_e32 v100, 0x3e38aa3b, v100
	v_max_f32_e32 v101, v105, v105
	v_max_f32_e32 v100, v101, v100
	v_add_f32_e32 v101, 8.0, v105
	v_cmp_gt_f32_e32 vcc, v100, v101
	s_cbranch_vccnz .Llz_0
	v_mov_b32_e32 v100, v105
	s_branch .LBB0_414
.Llz_0:
	v_sub_f32_e32 v101, v105, v100
	v_exp_f32_e32 v106, v101
	v_mov_b32_e32 v105, v100
	v_pk_mul_f32 v[32:33], v[32:33], v[106:107] op_sel_hi:[1,0]
	v_pk_mul_f32 v[30:31], v[30:31], v[106:107] op_sel_hi:[1,0]
	v_pk_mul_f32 v[28:29], v[28:29], v[106:107] op_sel_hi:[1,0]
	v_pk_mul_f32 v[26:27], v[26:27], v[106:107] op_sel_hi:[1,0]
	v_pk_mul_f32 v[24:25], v[24:25], v[106:107] op_sel_hi:[1,0]
	v_pk_mul_f32 v[22:23], v[22:23], v[106:107] op_sel_hi:[1,0]
	v_pk_mul_f32 v[20:21], v[20:21], v[106:107] op_sel_hi:[1,0]
	v_pk_mul_f32 v[18:19], v[18:19], v[106:107] op_sel_hi:[1,0]
	v_pk_mul_f32 v[16:17], v[16:17], v[106:107] op_sel_hi:[1,0]
	v_pk_mul_f32 v[14:15], v[14:15], v[106:107] op_sel_hi:[1,0]
	v_pk_mul_f32 v[12:13], v[12:13], v[106:107] op_sel_hi:[1,0]
	v_pk_mul_f32 v[10:11], v[10:11], v[106:107] op_sel_hi:[1,0]
	v_pk_mul_f32 v[8:9], v[8:9], v[106:107] op_sel_hi:[1,0]
	v_pk_mul_f32 v[6:7], v[6:7], v[106:107] op_sel_hi:[1,0]
	v_pk_mul_f32 v[4:5], v[4:5], v[106:107] op_sel_hi:[1,0]
	v_pk_mul_f32 v[2:3], v[2:3], v[106:107] op_sel_hi:[1,0]
	v_mul_f32_e32 v95, v95, v106
	s_branch .LBB0_414
.LBB0_417:
	s_barrier
	s_waitcnt vmcnt(1)
	ds_write_b128 v94, v[82:85]
	s_waitcnt vmcnt(0)
	ds_write_b128 v94, v[86:89] offset:18432
	s_waitcnt lgkmcnt(0)
	s_barrier
	ds_read_b128 v[34:37], v103
	ds_read_b128 v[38:41], v103 offset:32
	s_waitcnt lgkmcnt(1)
	v_mfma_f32_32x32x16_bf16 v[50:65], v[34:37], v[78:81], 0
	ds_read_b128 v[34:37], v103 offset:64
	s_waitcnt lgkmcnt(1)
	v_mfma_f32_32x32x16_bf16 v[50:65], v[38:41], v[74:77], v[50:65]
	s_waitcnt lgkmcnt(0)
	v_mfma_f32_32x32x16_bf16 v[50:65], v[34:37], v[70:73], v[50:65]
	ds_read_b128 v[34:37], v103 offset:96
	s_waitcnt lgkmcnt(0)
	v_mfma_f32_32x32x16_bf16 v[50:65], v[34:37], v[66:69], v[50:65]
	ds_read_b128 v[34:37], v103 offset:4608
	s_waitcnt lgkmcnt(0)
	v_mfma_f32_32x32x16_bf16 v[34:49], v[34:37], v[78:81], 0
	ds_read_b128 v[78:81], v103 offset:4640
	s_waitcnt lgkmcnt(0)
	v_mfma_f32_32x32x16_bf16 v[34:49], v[78:81], v[74:77], v[34:49]
	ds_read_b128 v[74:77], v103 offset:4672
	s_waitcnt lgkmcnt(0)
	v_mfma_f32_32x32x16_bf16 v[34:49], v[74:77], v[70:73], v[34:49]
	ds_read_b128 v[70:73], v103 offset:4704
	s_waitcnt lgkmcnt(0)
	v_mfma_f32_32x32x16_bf16 v[34:49], v[70:73], v[66:69], v[34:49]
	v_max3_f32 v66, v50, s33, v51
	v_max3_f32 v66, v66, v52, v53
	v_max3_f32 v66, v66, v54, v55
	v_max3_f32 v66, v66, v56, v57
	v_max3_f32 v66, v66, v58, v59
	v_max3_f32 v66, v66, v60, v61
	v_max3_f32 v66, v66, v62, v63
	v_max3_f32 v66, v66, v64, v65
	s_nop 3
	v_max3_f32 v66, v66, v34, v35
	v_max3_f32 v66, v66, v36, v37
	v_max3_f32 v66, v66, v38, v39
	v_max3_f32 v66, v66, v40, v41
	v_max3_f32 v66, v66, v42, v43
	v_max3_f32 v66, v66, v44, v45
	v_max3_f32 v66, v66, v46, v47
	v_max3_f32 v66, v66, v48, v49
	ds_bpermute_b32 v67, v93, v66
	s_waitcnt lgkmcnt(0)
	v_max_f32_e32 v67, v67, v67
	v_max_f32_e32 v66, v66, v67
	v_mul_f32_e32 v66, 0x3e38aa3b, v66
	v_max_f32_e32 v67, v105, v105
	v_max_f32_e32 v66, v67, v66
	v_add_f32_e32 v67, 8.0, v105
	v_cmp_gt_f32_e32 vcc, v66, v67
	s_cbranch_vccnz .Llz_1
	v_mov_b32_e32 v66, v105
	s_branch .LBB0_419
.Llz_1:
	v_sub_f32_e32 v67, v105, v66
	v_exp_f32_e32 v68, v67
	s_nop 0
	v_pk_mul_f32 v[32:33], v[32:33], v[68:69] op_sel_hi:[1,0]
	v_pk_mul_f32 v[30:31], v[30:31], v[68:69] op_sel_hi:[1,0]
	v_pk_mul_f32 v[28:29], v[28:29], v[68:69] op_sel_hi:[1,0]
	v_pk_mul_f32 v[26:27], v[26:27], v[68:69] op_sel_hi:[1,0]
	v_pk_mul_f32 v[24:25], v[24:25], v[68:69] op_sel_hi:[1,0]
	v_pk_mul_f32 v[22:23], v[22:23], v[68:69] op_sel_hi:[1,0]
	v_pk_mul_f32 v[20:21], v[20:21], v[68:69] op_sel_hi:[1,0]
	v_pk_mul_f32 v[18:19], v[18:19], v[68:69] op_sel_hi:[1,0]
	v_pk_mul_f32 v[16:17], v[16:17], v[68:69] op_sel_hi:[1,0]
	v_pk_mul_f32 v[14:15], v[14:15], v[68:69] op_sel_hi:[1,0]
	v_pk_mul_f32 v[12:13], v[12:13], v[68:69] op_sel_hi:[1,0]
	v_pk_mul_f32 v[10:11], v[10:11], v[68:69] op_sel_hi:[1,0]
	v_pk_mul_f32 v[8:9], v[8:9], v[68:69] op_sel_hi:[1,0]
	v_pk_mul_f32 v[6:7], v[6:7], v[68:69] op_sel_hi:[1,0]
	v_pk_mul_f32 v[4:5], v[4:5], v[68:69] op_sel_hi:[1,0]
	v_pk_mul_f32 v[2:3], v[2:3], v[68:69] op_sel_hi:[1,0]
	v_mul_f32_e32 v95, v95, v68

; DI f32x16 mfma32(bf8 a, bf8 b, f32x16 c) { return __builtin_amdgcn_mfma_f32_32x32x16_bf16(a, b, c, 0, 0, 0); }
; DI float ex2(float x) { return __builtin_amdgcn_exp2f(x); }
; DI float shx(float v, int lane, int mask) { return __int_as_float(__builtin_amdgcn_ds_bpermute((lane ^ mask) << 2, __float_as_int(v))); }
; DI void attn_item_q64(const AttnArgs& a, char* smem) {
;     ...
;   for (int tt = 0; tt < nt; ++tt) {
;     const char* Ks = Kb_ + (tt & 1) * 8192;
;     const char* Vs = Vb_ + (tt & 1) * 8192;
;     f32x16 s[2][2];
; #pragma unroll
;     for (int kb = 0; kb < 2; ++kb) {
; #pragma unroll
;       for (int q2 = 0; q2 < 2; ++q2)
; #pragma unroll
;         for (int i = 0; i < 16; ++i) s[q2][kb][i] = 0.f;
; #pragma unroll
;       for (int ks = 0; ks < 4; ++ks) {
;         const bf8 kf = *(const bf8*)(Ks + kb * 32 * 128 + koff[ks]);
; #pragma unroll
;         for (int q2 = 0; q2 < 2; ++q2) s[q2][kb] = mfma32(kf, qf[q2][ks], s[q2][kb]);
;       }
;     }
;     constexpr float SC = 0.125f * LOG2E;
; #pragma unroll
;     for (int q2 = 0; q2 < 2; ++q2) {
;       float mx = -INFINITY;
; #pragma unroll
;       for (int kb = 0; kb < 2; ++kb)
; #pragma unroll
;         for (int i = 0; i < 16; i += 2) mx = fmaxf(fmaxf(mx, s[q2][kb][i]), s[q2][kb][i + 1]);
;       mx = fmaxf(mx, shx(mx, lane, 32)) * SC;
;       const float mn = fmaxf(m[q2], mx);
;       const bool resc = __builtin_amdgcn_ballot_w64(mn != m[q2]) != 0ull;
;       float ps0 = 0.f, ps1 = 0.f;
; #pragma unroll
;       for (int kb = 0; kb < 2; ++kb)
; #pragma unroll
;         for (int i = 0; i < 16; i += 2) {
;           f32x2n v = {s[q2][kb][i], s[q2][kb][i + 1]};
;           v = v * f32x2n{SC, SC} - f32x2n{mn, mn};
;           const float p0 = ex2(v.x), p1 = ex2(v.y);
;           s[q2][kb][i] = p0; s[q2][kb][i + 1] = p1;
;           ps0 += p0; ps1 += p1;
;         }
;       if (resc) {
;         const float alpha = ex2(m[q2] - mn);
;         m[q2] = mn;
;         lsum[q2] *= alpha;
; #pragma unroll
;         for (int d = 0; d < 2; ++d)
; #pragma unroll
;           for (int i = 0; i < 16; ++i) O[q2][d][i] *= alpha;
;       }
.LBB0_423:
	s_and_b32 s14, s2, 0x2000
	v_or_b32_e32 v0, s14, v176
	s_waitcnt vmcnt(19)
	ds_read_b128 v[66:69], v0
	v_or_b32_e32 v172, s14, v177
	s_waitcnt vmcnt(17)
	ds_read_b128 v[82:85], v172
	v_or_b32_e32 v196, s14, v178
	v_or_b32_e32 v197, s14, v179
	ds_read_b128 v[192:195], v172 offset:4096
	s_waitcnt vmcnt(7) lgkmcnt(2)
	v_mfma_f32_32x32x16_bf16 v[98:113], v[66:69], v[130:133], 0
	s_waitcnt vmcnt(3)
	v_mfma_f32_32x32x16_bf16 v[66:81], v[66:69], v[146:149], 0
	s_waitcnt lgkmcnt(1)
	v_mfma_f32_32x32x16_bf16 v[98:113], v[82:85], v[134:137], v[98:113]
	s_waitcnt vmcnt(2)
	v_mfma_f32_32x32x16_bf16 v[66:81], v[82:85], v[150:153], v[66:81]
	ds_read_b128 v[82:85], v196
	s_waitcnt lgkmcnt(0)
	v_mfma_f32_32x32x16_bf16 v[98:113], v[82:85], v[138:141], v[98:113]
	s_waitcnt vmcnt(1)
	v_mfma_f32_32x32x16_bf16 v[66:81], v[82:85], v[154:157], v[66:81]
	ds_read_b128 v[82:85], v197
	s_waitcnt lgkmcnt(0)
	v_mfma_f32_32x32x16_bf16 v[98:113], v[82:85], v[142:145], v[98:113]
	s_waitcnt vmcnt(0)
	v_mfma_f32_32x32x16_bf16 v[66:81], v[82:85], v[158:161], v[66:81]
	ds_read_b128 v[82:85], v0 offset:4096
	s_nop 8
	v_max3_f32 v0, v98, s33, v99
	v_max3_f32 v0, v0, v100, v101
	v_max3_f32 v0, v0, v102, v103
	v_max3_f32 v0, v0, v104, v105
	v_max3_f32 v0, v0, v106, v107
	v_max3_f32 v0, v0, v108, v109
	s_waitcnt lgkmcnt(0)
	v_mfma_f32_32x32x16_bf16 v[114:129], v[82:85], v[130:133], 0
	v_max3_f32 v0, v0, v110, v111
	v_max3_f32 v0, v0, v112, v113
	v_mfma_f32_32x32x16_bf16 v[82:97], v[82:85], v[146:149], 0
	v_mfma_f32_32x32x16_bf16 v[114:129], v[192:195], v[134:137], v[114:129]
	v_mfma_f32_32x32x16_bf16 v[82:97], v[192:195], v[150:153], v[82:97]
	ds_read_b128 v[192:195], v196 offset:4096
	s_waitcnt lgkmcnt(0)
	v_mfma_f32_32x32x16_bf16 v[114:129], v[192:195], v[138:141], v[114:129]
	v_mfma_f32_32x32x16_bf16 v[82:97], v[192:195], v[154:157], v[82:97]
	ds_read_b128 v[192:195], v197 offset:4096
	s_waitcnt lgkmcnt(0)
	v_mfma_f32_32x32x16_bf16 v[114:129], v[192:195], v[142:145], v[114:129]
	v_mfma_f32_32x32x16_bf16 v[82:97], v[192:195], v[158:161], v[82:97]
	s_nop 10
	v_max3_f32 v0, v0, v114, v115
	v_max3_f32 v0, v0, v116, v117
	v_max3_f32 v0, v0, v118, v119
	v_max3_f32 v0, v0, v120, v121
	v_max3_f32 v0, v0, v122, v123
	v_max3_f32 v0, v0, v124, v125
	v_max3_f32 v0, v0, v126, v127
	v_max3_f32 v0, v0, v128, v129
	ds_bpermute_b32 v172, v173, v0
	s_waitcnt lgkmcnt(0)
	v_max_f32_e32 v172, v172, v172
	v_max_f32_e32 v0, v0, v172
	v_mul_f32_e32 v0, 0x3e38aa3b, v0
	v_max_f32_e32 v172, v191, v191
	v_max_f32_e32 v0, v172, v0
	v_add_f32_e32 v172, 8.0, v191
	v_cmp_gt_f32_e32 vcc, v0, v172
	s_cbranch_vccnz .Llz_2
	v_mov_b32_e32 v0, v191
	s_branch .LBB0_425
.Llz_2:
	v_sub_f32_e32 v172, v191, v0
	v_exp_f32_e32 v172, v172
	v_mov_b32_e32 v191, v0
	v_mul_f32_e32 v189, v189, v172
	v_pk_mul_f32 v[64:65], v[64:65], v[172:173] op_sel_hi:[1,0]
	v_pk_mul_f32 v[62:63], v[62:63], v[172:173] op_sel_hi:[1,0]
	v_pk_mul_f32 v[60:61], v[60:61], v[172:173] op_sel_hi:[1,0]
	v_pk_mul_f32 v[58:59], v[58:59], v[172:173] op_sel_hi:[1,0]
	v_pk_mul_f32 v[56:57], v[56:57], v[172:173] op_sel_hi:[1,0]
	v_pk_mul_f32 v[54:55], v[54:55], v[172:173] op_sel_hi:[1,0]
	v_pk_mul_f32 v[52:53], v[52:53], v[172:173] op_sel_hi:[1,0]
	v_pk_mul_f32 v[50:51], v[50:51], v[172:173] op_sel_hi:[1,0]
	v_pk_mul_f32 v[48:49], v[48:49], v[172:173] op_sel_hi:[1,0]
	v_pk_mul_f32 v[46:47], v[46:47], v[172:173] op_sel_hi:[1,0]
	v_pk_mul_f32 v[44:45], v[44:45], v[172:173] op_sel_hi:[1,0]
	v_pk_mul_f32 v[42:43], v[42:43], v[172:173] op_sel_hi:[1,0]
	v_pk_mul_f32 v[40:41], v[40:41], v[172:173] op_sel_hi:[1,0]
	v_pk_mul_f32 v[38:39], v[38:39], v[172:173] op_sel_hi:[1,0]
	v_pk_mul_f32 v[36:37], v[36:37], v[172:173] op_sel_hi:[1,0]
	v_pk_mul_f32 v[34:35], v[34:35], v[172:173] op_sel_hi:[1,0]
.LBB0_425:
	v_max3_f32 v172, v66, s33, v67
	v_max3_f32 v172, v172, v68, v69
	v_max3_f32 v172, v172, v70, v71
	v_max3_f32 v172, v172, v72, v73
	v_max3_f32 v172, v172, v74, v75
	v_max3_f32 v172, v172, v76, v77
	v_max3_f32 v172, v172, v78, v79
	v_max3_f32 v172, v172, v80, v81
	v_max3_f32 v172, v172, v82, v83
	v_max3_f32 v172, v172, v84, v85
	v_max3_f32 v172, v172, v86, v87
	v_max3_f32 v172, v172, v88, v89
	v_max3_f32 v172, v172, v90, v91
	v_max3_f32 v172, v172, v92, v93
	v_max3_f32 v172, v172, v94, v95
	v_max3_f32 v172, v172, v96, v97
	ds_bpermute_b32 v192, v173, v172
	s_waitcnt lgkmcnt(0)
	v_max_f32_e32 v192, v192, v192
	v_max_f32_e32 v172, v172, v192
	v_mul_f32_e32 v172, 0x3e38aa3b, v172
	v_max_f32_e32 v192, v190, v190
	v_max_f32_e32 v172, v192, v172
	v_add_f32_e32 v192, 8.0, v190
	v_cmp_gt_f32_e32 vcc, v172, v192
	s_cbranch_vccnz .Llz_3
	v_mov_b32_e32 v172, v190
	s_branch .LBB0_427
.Llz_3:
	v_sub_f32_e32 v190, v190, v172
	v_exp_f32_e32 v190, v190
	s_nop 0
	v_mul_f32_e32 v174, v174, v190
	v_pk_mul_f32 v[32:33], v[32:33], v[190:191] op_sel_hi:[1,0]
	v_pk_mul_f32 v[30:31], v[30:31], v[190:191] op_sel_hi:[1,0]
	v_pk_mul_f32 v[28:29], v[28:29], v[190:191] op_sel_hi:[1,0]
	v_pk_mul_f32 v[26:27], v[26:27], v[190:191] op_sel_hi:[1,0]
	v_pk_mul_f32 v[24:25], v[24:25], v[190:191] op_sel_hi:[1,0]
	v_pk_mul_f32 v[22:23], v[22:23], v[190:191] op_sel_hi:[1,0]
	v_pk_mul_f32 v[20:21], v[20:21], v[190:191] op_sel_hi:[1,0]
	v_pk_mul_f32 v[18:19], v[18:19], v[190:191] op_sel_hi:[1,0]
	v_pk_mul_f32 v[16:17], v[16:17], v[190:191] op_sel_hi:[1,0]
	v_pk_mul_f32 v[14:15], v[14:15], v[190:191] op_sel_hi:[1,0]
	v_pk_mul_f32 v[12:13], v[12:13], v[190:191] op_sel_hi:[1,0]
	v_pk_mul_f32 v[10:11], v[10:11], v[190:191] op_sel_hi:[1,0]
	v_pk_mul_f32 v[8:9], v[8:9], v[190:191] op_sel_hi:[1,0]
	v_pk_mul_f32 v[6:7], v[6:7], v[190:191] op_sel_hi:[1,0]
	v_pk_mul_f32 v[4:5], v[4:5], v[190:191] op_sel_hi:[1,0]
	v_pk_mul_f32 v[2:3], v[2:3], v[190:191] op_sel_hi:[1,0]
	v_mov_b32_e32 v190, v172

; DI int crow(int i, int h) { return (i & 3) + 8 * (i >> 2) + 4 * h; }
; DI f32x16 mfma32(bf8 a, bf8 b, f32x16 c) { return __builtin_amdgcn_mfma_f32_32x32x16_bf16(a, b, c, 0, 0, 0); }
; DI float ex2(float x) { return __builtin_amdgcn_exp2f(x); }
; template <int DV, int MODE>
; DI void attn_item(const AttnArgs& a, char* smem) {
;     ...
;       f32x16 s[2];
; #pragma unroll
;       for (int kb = 0; kb < 2; ++kb) {
; #pragma unroll
;         for (int i = 0; i < 16; ++i) s[kb][i] = 0.f;
; #pragma unroll
;         for (int ks = 0; ks < 4; ++ks) {
;           const bf8 kf = *(const bf8*)(Ks + (kb * 32 + r) * 72 + ks * 16 + h * 8);
;           s[kb] = mfma32(kf, qf[ks], s[kb]);
;         }
;       }
;       constexpr float SC = 0.125f * LOG2E;
;       float mx = -INFINITY;
;       if (local) {
; #pragma unroll
;         for (int kb = 0; kb < 2; ++kb)
; #pragma unroll
;           for (int i = 0; i < 16; ++i) {
;             const int kc = kb * 32 + crow(i, h);
;             const bool ok = (kc >= cs) && (kc < cs + 16);
;             const int dc = kc - qc + 15;
;             const int dr = kr - rq + 7;
;             const float bias = rpbS[dr * 32 + (ok ? dc : 0)];
;             const float v = ok ? (s[kb][i] + bias * (1.f / SC)) : -INFINITY;
;             s[kb][i] = v;
;             mx = fmaxf(mx, v);
;           }
;       } else {
; #pragma unroll
;         for (int kb = 0; kb < 2; ++kb)
; #pragma unroll
;           for (int i = 0; i < 16; i += 2) mx = fmaxf(fmaxf(mx, s[kb][i]), s[kb][i + 1]);
;       }
;       mx = fmaxf(mx, shx(mx, lane, 32)) * SC;
;       const float mn = fmaxf(m, mx);
;       const bool resc = __builtin_amdgcn_ballot_w64(mn != m) != 0ull;
;       float ps0 = 0.f, ps1 = 0.f;
; #pragma unroll
;       for (int kb = 0; kb < 2; ++kb)
; #pragma unroll
;         for (int i = 0; i < 16; i += 2) {
;           f32x2n v = {s[kb][i], s[kb][i + 1]};
;           v = v * f32x2n{SC, SC} - f32x2n{mn, mn};
;           const float p0 = ex2(v.x), p1 = ex2(v.y);
;           s[kb][i] = p0; s[kb][i + 1] = p1;
;           ps0 += p0; ps1 += p1;
;         }
;       if (resc) {
;         const float alpha = ex2(m - mn);
;         m = mn;
;         lsum *= alpha;
; #pragma unroll
;         for (int d = 0; d < NDV; ++d)
; #pragma unroll
;           for (int i = 0; i < 16; ++i) O[d][i] *= alpha;
;       }
.LBB0_441:
	ds_read_b128 v[66:69], v146
	ds_read_b128 v[70:73], v146 offset:32
	ds_read_b128 v[150:153], v146 offset:4640
	s_waitcnt lgkmcnt(2)
	v_mfma_f32_32x32x16_bf16 v[82:97], v[66:69], v[98:101], 0
	ds_read_b128 v[66:69], v146 offset:64
	s_waitcnt lgkmcnt(2)
	v_mfma_f32_32x32x16_bf16 v[82:97], v[70:73], v[102:105], v[82:97]
	s_waitcnt lgkmcnt(0)
	v_mfma_f32_32x32x16_bf16 v[82:97], v[66:69], v[106:109], v[82:97]
	ds_read_b128 v[66:69], v146 offset:96
	s_waitcnt lgkmcnt(0)
	v_mfma_f32_32x32x16_bf16 v[82:97], v[66:69], v[110:113], v[82:97]
	ds_read_b128 v[66:69], v146 offset:4608
	s_waitcnt lgkmcnt(0)
	v_mfma_f32_32x32x16_bf16 v[66:81], v[66:69], v[98:101], 0
	s_nop 8
	v_max3_f32 v142, v82, s33, v83
	v_max3_f32 v142, v142, v84, v85
	v_max3_f32 v142, v142, v86, v87
	v_max3_f32 v142, v142, v88, v89
	v_max3_f32 v142, v142, v90, v91
	v_max3_f32 v142, v142, v92, v93
	v_max3_f32 v142, v142, v94, v95
	v_mfma_f32_32x32x16_bf16 v[66:81], v[150:153], v[102:105], v[66:81]
	ds_read_b128 v[150:153], v146 offset:4672
	v_max3_f32 v142, v142, v96, v97
	s_waitcnt lgkmcnt(0)
	v_mfma_f32_32x32x16_bf16 v[66:81], v[150:153], v[106:109], v[66:81]
	ds_read_b128 v[150:153], v146 offset:4704
	s_waitcnt lgkmcnt(0)
	v_mfma_f32_32x32x16_bf16 v[66:81], v[150:153], v[110:113], v[66:81]
	s_nop 11
	v_max3_f32 v142, v142, v66, v67
	v_max3_f32 v142, v142, v68, v69
	v_max3_f32 v142, v142, v70, v71
	v_max3_f32 v142, v142, v72, v73
	v_max3_f32 v142, v142, v74, v75
	v_max3_f32 v142, v142, v76, v77
	v_max3_f32 v142, v142, v78, v79
	v_max3_f32 v142, v142, v80, v81
	ds_bpermute_b32 v150, v133, v142
	s_waitcnt lgkmcnt(0)
	v_max_f32_e32 v150, v150, v150
	v_max_f32_e32 v142, v142, v150
	v_mul_f32_e32 v142, 0x3e38aa3b, v142
	v_max_f32_e32 v150, v148, v148
	v_max_f32_e32 v142, v150, v142
	v_add_f32_e32 v150, 8.0, v148
	v_cmp_gt_f32_e32 vcc, v142, v150
	s_cbranch_vccnz .Llz_4
	v_mov_b32_e32 v142, v148
	s_branch .LBB0_438
.Llz_4:
	v_sub_f32_e32 v148, v148, v142
	v_exp_f32_e32 v148, v148
	s_nop 0
	v_pk_mul_f32 v[64:65], v[64:65], v[148:149] op_sel_hi:[1,0]
	v_pk_mul_f32 v[62:63], v[62:63], v[148:149] op_sel_hi:[1,0]
	v_pk_mul_f32 v[60:61], v[60:61], v[148:149] op_sel_hi:[1,0]
	v_pk_mul_f32 v[58:59], v[58:59], v[148:149] op_sel_hi:[1,0]
	v_pk_mul_f32 v[56:57], v[56:57], v[148:149] op_sel_hi:[1,0]
	v_pk_mul_f32 v[54:55], v[54:55], v[148:149] op_sel_hi:[1,0]
	v_pk_mul_f32 v[52:53], v[52:53], v[148:149] op_sel_hi:[1,0]
	v_pk_mul_f32 v[50:51], v[50:51], v[148:149] op_sel_hi:[1,0]
	v_pk_mul_f32 v[48:49], v[48:49], v[148:149] op_sel_hi:[1,0]
	v_pk_mul_f32 v[46:47], v[46:47], v[148:149] op_sel_hi:[1,0]
	v_pk_mul_f32 v[44:45], v[44:45], v[148:149] op_sel_hi:[1,0]
	v_pk_mul_f32 v[42:43], v[42:43], v[148:149] op_sel_hi:[1,0]
	v_pk_mul_f32 v[40:41], v[40:41], v[148:149] op_sel_hi:[1,0]
	v_pk_mul_f32 v[38:39], v[38:39], v[148:149] op_sel_hi:[1,0]
	v_pk_mul_f32 v[36:37], v[36:37], v[148:149] op_sel_hi:[1,0]
	v_pk_mul_f32 v[34:35], v[34:35], v[148:149] op_sel_hi:[1,0]
	v_pk_mul_f32 v[32:33], v[32:33], v[148:149] op_sel_hi:[1,0]
	v_pk_mul_f32 v[30:31], v[30:31], v[148:149] op_sel_hi:[1,0]
	v_pk_mul_f32 v[28:29], v[28:29], v[148:149] op_sel_hi:[1,0]
	v_pk_mul_f32 v[26:27], v[26:27], v[148:149] op_sel_hi:[1,0]
	v_pk_mul_f32 v[24:25], v[24:25], v[148:149] op_sel_hi:[1,0]
	v_pk_mul_f32 v[22:23], v[22:23], v[148:149] op_sel_hi:[1,0]
	v_pk_mul_f32 v[20:21], v[20:21], v[148:149] op_sel_hi:[1,0]
	v_pk_mul_f32 v[18:19], v[18:19], v[148:149] op_sel_hi:[1,0]
	v_pk_mul_f32 v[16:17], v[16:17], v[148:149] op_sel_hi:[1,0]
	v_pk_mul_f32 v[14:15], v[14:15], v[148:149] op_sel_hi:[1,0]
	v_pk_mul_f32 v[12:13], v[12:13], v[148:149] op_sel_hi:[1,0]
	v_pk_mul_f32 v[10:11], v[10:11], v[148:149] op_sel_hi:[1,0]
	v_pk_mul_f32 v[8:9], v[8:9], v[148:149] op_sel_hi:[1,0]
	v_pk_mul_f32 v[6:7], v[6:7], v[148:149] op_sel_hi:[1,0]
	v_pk_mul_f32 v[4:5], v[4:5], v[148:149] op_sel_hi:[1,0]
	v_pk_mul_f32 v[2:3], v[2:3], v[148:149] op_sel_hi:[1,0]
	v_mul_f32_e32 v145, v145, v148
	v_mov_b32_e32 v148, v142
	s_branch .LBB0_438

; DI float ex2(float x) { return __builtin_amdgcn_exp2f(x); }
; DI float shx(float v, int lane, int mask) { return __int_as_float(__builtin_amdgcn_ds_bpermute((lane ^ mask) << 2, __float_as_int(v))); }
; template <int DV, int MODE>
; DI void attn_item(const AttnArgs& a, char* smem) {
;     ...
;       mx = fmaxf(mx, shx(mx, lane, 32)) * SC;
;       const float mn = fmaxf(m, mx);
;       const bool resc = __builtin_amdgcn_ballot_w64(mn != m) != 0ull;
;       float ps0 = 0.f, ps1 = 0.f;
; #pragma unroll
;       for (int kb = 0; kb < 2; ++kb)
; #pragma unroll
;         for (int i = 0; i < 16; i += 2) {
;           f32x2n v = {s[kb][i], s[kb][i + 1]};
;           v = v * f32x2n{SC, SC} - f32x2n{mn, mn};
;           const float p0 = ex2(v.x), p1 = ex2(v.y);
;           s[kb][i] = p0; s[kb][i + 1] = p1;
;           ps0 += p0; ps1 += p1;
;         }
;       if (resc) {
;         const float alpha = ex2(m - mn);
;         m = mn;
;         lsum *= alpha;
; #pragma unroll
;         for (int d = 0; d < NDV; ++d)
; #pragma unroll
;           for (int i = 0; i < 16; ++i) O[d][i] *= alpha;
;       }
.LBB0_542:
	ds_bpermute_b32 v34, v133, v141
	v_max_f32_e32 v35, v141, v141
	s_waitcnt lgkmcnt(0)
	v_max_f32_e32 v34, v34, v34
	v_max_f32_e32 v34, v35, v34
	v_mul_f32_e32 v34, 0x3e38aa3b, v34
	v_max_f32_e32 v35, v140, v140
	v_max_f32_e32 v34, v35, v34
	v_add_f32_e32 v35, 8.0, v140
	v_cmp_gt_f32_e32 vcc, v34, v35
	s_cbranch_vccnz .Llz_7
	v_mov_b32_e32 v34, v140
	s_branch .LBB0_544
.Llz_7:
	v_sub_f32_e32 v35, v140, v34
	v_exp_f32_e32 v36, v35
	v_mov_b32_e32 v140, v34
	v_pk_mul_f32 v[32:33], v[32:33], v[36:37] op_sel_hi:[1,0]
	v_pk_mul_f32 v[30:31], v[30:31], v[36:37] op_sel_hi:[1,0]
	v_pk_mul_f32 v[28:29], v[28:29], v[36:37] op_sel_hi:[1,0]
	v_pk_mul_f32 v[26:27], v[26:27], v[36:37] op_sel_hi:[1,0]
	v_pk_mul_f32 v[24:25], v[24:25], v[36:37] op_sel_hi:[1,0]
	v_pk_mul_f32 v[22:23], v[22:23], v[36:37] op_sel_hi:[1,0]
	v_pk_mul_f32 v[20:21], v[20:21], v[36:37] op_sel_hi:[1,0]
	v_pk_mul_f32 v[18:19], v[18:19], v[36:37] op_sel_hi:[1,0]
	v_pk_mul_f32 v[16:17], v[16:17], v[36:37] op_sel_hi:[1,0]
	v_pk_mul_f32 v[14:15], v[14:15], v[36:37] op_sel_hi:[1,0]
	v_pk_mul_f32 v[12:13], v[12:13], v[36:37] op_sel_hi:[1,0]
	v_pk_mul_f32 v[10:11], v[10:11], v[36:37] op_sel_hi:[1,0]
	v_pk_mul_f32 v[8:9], v[8:9], v[36:37] op_sel_hi:[1,0]
	v_pk_mul_f32 v[6:7], v[6:7], v[36:37] op_sel_hi:[1,0]
	v_pk_mul_f32 v[4:5], v[4:5], v[36:37] op_sel_hi:[1,0]
	v_pk_mul_f32 v[2:3], v[2:3], v[36:37] op_sel_hi:[1,0]
	v_mul_f32_e32 v137, v137, v36

; DI int crow(int i, int h) { return (i & 3) + 8 * (i >> 2) + 4 * h; }
; DI f32x16 mfma32(bf8 a, bf8 b, f32x16 c) { return __builtin_amdgcn_mfma_f32_32x32x16_bf16(a, b, c, 0, 0, 0); }
; DI float ex2(float x) { return __builtin_amdgcn_exp2f(x); }
; template <int DV, int MODE>
; DI void attn_item(const AttnArgs& a, char* smem) {
;     ...
;       f32x16 s[2];
; #pragma unroll
;       for (int kb = 0; kb < 2; ++kb) {
; #pragma unroll
;         for (int i = 0; i < 16; ++i) s[kb][i] = 0.f;
; #pragma unroll
;         for (int ks = 0; ks < 4; ++ks) {
;           const bf8 kf = *(const bf8*)(Ks + (kb * 32 + r) * 72 + ks * 16 + h * 8);
;           s[kb] = mfma32(kf, qf[ks], s[kb]);
;         }
;       }
;       constexpr float SC = 0.125f * LOG2E;
;       float mx = -INFINITY;
;       if (local) {
; #pragma unroll
;         for (int kb = 0; kb < 2; ++kb)
; #pragma unroll
;           for (int i = 0; i < 16; ++i) {
;             const int kc = kb * 32 + crow(i, h);
;             const bool ok = (kc >= cs) && (kc < cs + 16);
;             const int dc = kc - qc + 15;
;             const int dr = kr - rq + 7;
;             const float bias = rpbS[dr * 32 + (ok ? dc : 0)];
;             const float v = ok ? (s[kb][i] + bias * (1.f / SC)) : -INFINITY;
;             s[kb][i] = v;
;             mx = fmaxf(mx, v);
;           }
;       } else {
; #pragma unroll
;         for (int kb = 0; kb < 2; ++kb)
; #pragma unroll
;           for (int i = 0; i < 16; i += 2) mx = fmaxf(fmaxf(mx, s[kb][i]), s[kb][i + 1]);
;       }
;       mx = fmaxf(mx, shx(mx, lane, 32)) * SC;
;       const float mn = fmaxf(m, mx);
;       const bool resc = __builtin_amdgcn_ballot_w64(mn != m) != 0ull;
;       float ps0 = 0.f, ps1 = 0.f;
; #pragma unroll
;       for (int kb = 0; kb < 2; ++kb)
; #pragma unroll
;         for (int i = 0; i < 16; i += 2) {
;           f32x2n v = {s[kb][i], s[kb][i + 1]};
;           v = v * f32x2n{SC, SC} - f32x2n{mn, mn};
;           const float p0 = ex2(v.x), p1 = ex2(v.y);
;           s[kb][i] = p0; s[kb][i + 1] = p1;
;           ps0 += p0; ps1 += p1;
;         }
;       if (resc) {
;         const float alpha = ex2(m - mn);
;         m = mn;
;         lsum *= alpha;
; #pragma unroll
;         for (int d = 0; d < NDV; ++d)
; #pragma unroll
;           for (int i = 0; i < 16; ++i) O[d][i] *= alpha;
;       }
.LBB0_556:
	ds_read_b128 v[66:69], v153
	ds_read_b128 v[70:73], v153 offset:32
	ds_read_b128 v[156:159], v153 offset:4640
	s_waitcnt lgkmcnt(2)
	v_mfma_f32_32x32x16_bf16 v[82:97], v[66:69], v[98:101], 0
	ds_read_b128 v[66:69], v153 offset:64
	s_waitcnt lgkmcnt(2)
	v_mfma_f32_32x32x16_bf16 v[82:97], v[70:73], v[102:105], v[82:97]
	s_waitcnt lgkmcnt(0)
	v_mfma_f32_32x32x16_bf16 v[82:97], v[66:69], v[106:109], v[82:97]
	ds_read_b128 v[66:69], v153 offset:96
	s_waitcnt lgkmcnt(0)
	v_mfma_f32_32x32x16_bf16 v[82:97], v[66:69], v[110:113], v[82:97]
	ds_read_b128 v[66:69], v153 offset:4608
	s_waitcnt lgkmcnt(0)
	v_mfma_f32_32x32x16_bf16 v[66:81], v[66:69], v[98:101], 0
	s_nop 8
	v_max3_f32 v148, v82, s33, v83
	v_max3_f32 v148, v148, v84, v85
	v_max3_f32 v148, v148, v86, v87
	v_max3_f32 v148, v148, v88, v89
	v_max3_f32 v148, v148, v90, v91
	v_max3_f32 v148, v148, v92, v93
	v_max3_f32 v148, v148, v94, v95
	v_mfma_f32_32x32x16_bf16 v[66:81], v[156:159], v[102:105], v[66:81]
	ds_read_b128 v[156:159], v153 offset:4672
	v_max3_f32 v148, v148, v96, v97
	s_waitcnt lgkmcnt(0)
	v_mfma_f32_32x32x16_bf16 v[66:81], v[156:159], v[106:109], v[66:81]
	ds_read_b128 v[156:159], v153 offset:4704
	s_waitcnt lgkmcnt(0)
	v_mfma_f32_32x32x16_bf16 v[66:81], v[156:159], v[110:113], v[66:81]
	s_nop 11
	v_max3_f32 v148, v148, v66, v67
	v_max3_f32 v148, v148, v68, v69
	v_max3_f32 v148, v148, v70, v71
	v_max3_f32 v148, v148, v72, v73
	v_max3_f32 v148, v148, v74, v75
	v_max3_f32 v148, v148, v76, v77
	v_max3_f32 v148, v148, v78, v79
	v_max3_f32 v148, v148, v80, v81
	ds_bpermute_b32 v156, v137, v148
	s_waitcnt lgkmcnt(0)
	v_max_f32_e32 v156, v156, v156
	v_max_f32_e32 v148, v148, v156
	v_mul_f32_e32 v148, 0x3e38aa3b, v148
	v_max_f32_e32 v156, v155, v155
	v_max_f32_e32 v148, v156, v148
	v_add_f32_e32 v156, 8.0, v155
	v_cmp_gt_f32_e32 vcc, v148, v156
	s_cbranch_vccnz .Llz_8
	v_mov_b32_e32 v148, v155
	s_branch .LBB0_553
.Llz_8:
	v_sub_f32_e32 v155, v155, v148
	v_exp_f32_e32 v156, v155
	v_mov_b32_e32 v155, v148
	v_pk_mul_f32 v[64:65], v[64:65], v[156:157] op_sel_hi:[1,0]
	v_pk_mul_f32 v[62:63], v[62:63], v[156:157] op_sel_hi:[1,0]
	v_pk_mul_f32 v[60:61], v[60:61], v[156:157] op_sel_hi:[1,0]
	v_pk_mul_f32 v[58:59], v[58:59], v[156:157] op_sel_hi:[1,0]
	v_pk_mul_f32 v[56:57], v[56:57], v[156:157] op_sel_hi:[1,0]
	v_pk_mul_f32 v[54:55], v[54:55], v[156:157] op_sel_hi:[1,0]
	v_pk_mul_f32 v[52:53], v[52:53], v[156:157] op_sel_hi:[1,0]
	v_pk_mul_f32 v[50:51], v[50:51], v[156:157] op_sel_hi:[1,0]
	v_pk_mul_f32 v[48:49], v[48:49], v[156:157] op_sel_hi:[1,0]
	v_pk_mul_f32 v[46:47], v[46:47], v[156:157] op_sel_hi:[1,0]
	v_pk_mul_f32 v[44:45], v[44:45], v[156:157] op_sel_hi:[1,0]
	v_pk_mul_f32 v[42:43], v[42:43], v[156:157] op_sel_hi:[1,0]
	v_pk_mul_f32 v[40:41], v[40:41], v[156:157] op_sel_hi:[1,0]
	v_pk_mul_f32 v[38:39], v[38:39], v[156:157] op_sel_hi:[1,0]
	v_pk_mul_f32 v[36:37], v[36:37], v[156:157] op_sel_hi:[1,0]
	v_pk_mul_f32 v[34:35], v[34:35], v[156:157] op_sel_hi:[1,0]
	v_pk_mul_f32 v[32:33], v[32:33], v[156:157] op_sel_hi:[1,0]
	v_pk_mul_f32 v[30:31], v[30:31], v[156:157] op_sel_hi:[1,0]
	v_pk_mul_f32 v[28:29], v[28:29], v[156:157] op_sel_hi:[1,0]
	v_pk_mul_f32 v[26:27], v[26:27], v[156:157] op_sel_hi:[1,0]
	v_pk_mul_f32 v[24:25], v[24:25], v[156:157] op_sel_hi:[1,0]
	v_pk_mul_f32 v[22:23], v[22:23], v[156:157] op_sel_hi:[1,0]
	v_pk_mul_f32 v[20:21], v[20:21], v[156:157] op_sel_hi:[1,0]
	v_pk_mul_f32 v[18:19], v[18:19], v[156:157] op_sel_hi:[1,0]
	v_pk_mul_f32 v[16:17], v[16:17], v[156:157] op_sel_hi:[1,0]
	v_pk_mul_f32 v[14:15], v[14:15], v[156:157] op_sel_hi:[1,0]
	v_pk_mul_f32 v[12:13], v[12:13], v[156:157] op_sel_hi:[1,0]
	v_pk_mul_f32 v[10:11], v[10:11], v[156:157] op_sel_hi:[1,0]
	v_pk_mul_f32 v[8:9], v[8:9], v[156:157] op_sel_hi:[1,0]
	v_pk_mul_f32 v[6:7], v[6:7], v[156:157] op_sel_hi:[1,0]
	v_pk_mul_f32 v[4:5], v[4:5], v[156:157] op_sel_hi:[1,0]
	v_pk_mul_f32 v[2:3], v[2:3], v[156:157] op_sel_hi:[1,0]
	v_mul_f32_e32 v152, v152, v156
	s_branch .LBB0_553
